# MoE weight conversion of layers 2-3 remainder moved into idle waves 4-7 of the hyena long-conv fft32 sections (LDS-free item: permlane32 transpose); top-k phases 1-3 no longer convert
# baseline (speedup 1.0000x reference)
.LBB0_1141:
	s_or_b64 exec, exec, s[4:5]
	s_waitcnt lgkmcnt(0)
	s_barrier
	v_mov_b32_e32 v254, 0

.LBB0_1156:
	s_or_b64 exec, exec, vcc
	v_add_u32_e32 v254, 1, v254
	v_readlane_b32 s100, v255, 6
	s_nop 3
	s_cmp_lt_u32 s100, 4
	s_cbranch_scc1 .Llc_skip_b
	s_sub_i32 s100, s100, 4
	s_mul_i32 s101, s2, 0x80
	s_add_i32 s100, s100, s101
	v_add_u32_e32 v253, -1, v254
	v_lshl_add_u32 v252, v253, 2, s100
	v_cmp_gt_u32_e64 s[100:101], 32, v253
	v_mov_b32_e32 v251, 0x7f00
	s_nop 1
	v_cndmask_b32_e64 v251, 0, v251, s[100:101]
	v_cmp_lt_u32_e64 s[100:101], v252, v251
	s_nop 3
	s_cmp_eq_u64 s[100:101], 0
	s_cbranch_scc1 .Llc_skip_b
	v_add_u32_e32 v250, 0xc000, v252
	v_add_u32_e32 v249, 0x10100, v252
	v_mov_b32_e32 v236, 0xc00
	v_cmp_gt_u32_e64 s[100:101], v236, v252
	s_nop 1
	v_cndmask_b32_e64 v250, v249, v250, s[100:101]
	v_mov_b32_e32 v249, 0x12000
	v_cmp_ge_u32_e64 s[100:101], v250, v249
	v_mov_b32_e32 v248, 0x3bb00000
	v_mov_b32_e32 v247, 0x3db00000
	v_mov_b32_e32 v246, 0x2b00000
	v_mov_b32_e32 v245, 0x6b00000
	v_cndmask_b32_e64 v248, v248, v246, s[100:101]
	v_cndmask_b32_e64 v247, v247, v245, s[100:101]
	v_mov_b32_e32 v246, 32
	v_cndmask_b32_e64 v246, v246, 48, s[100:101]
	v_mov_b32_e32 v245, 0xc000
	v_cndmask_b32_e64 v245, v245, v249, s[100:101]
	v_sub_u32_e32 v250, v250, v245
	v_mov_b32_e32 v236, 0x4000
	v_cmp_le_u32_e64 s[100:101], v236, v250
	v_subrev_u32_e32 v249, 0x4000, v250
	v_lshrrev_b32_e32 v245, 10, v250
	v_lshrrev_b32_e32 v244, 9, v249
	v_and_b32_e32 v243, 0x3ff, v250
	v_cndmask_b32_e64 v245, v245, v244, s[100:101]
	v_lshrrev_b32_e32 v244, 9, v243
	v_cndmask_b32_e64 v244, v244, 0, s[100:101]
	v_cndmask_b32_e64 v243, v250, v249, s[100:101]
	v_and_b32_e32 v243, 0x1ff, v243
	v_lshrrev_b32_e32 v242, 5, v243
	v_and_b32_e32 v243, 31, v243
	v_mov_b32_e32 v236, 0xc8
	v_lshl_add_u32 v241, v244, 3, v236
	v_mov_b32_e32 v236, 0xd8
	v_cndmask_b32_e64 v241, v241, v236, s[100:101]
	v_lshlrev_b32_e32 v240, 21, v245
	v_add_u32_e32 v240, v240, v248
	v_lshlrev_b32_e32 v239, 20, v245
	v_add_u32_e32 v239, v239, v247
	v_cndmask_b32_e64 v240, v240, v239, s[100:101]
	v_lshrrev_b32_e32 v239, 2, v243
	v_lshlrev_b32_e32 v239, 8, v239
	v_lshl_add_u32 v239, v244, 7, v239
	v_and_b32_e32 v238, 3, v243
	v_lshl_add_u32 v239, v238, 5, v239
	v_lshlrev_b32_e32 v238, 5, v243
	v_cndmask_b32_e64 v239, v239, v238, s[100:101]
	v_and_b32_e32 v238, 63, v0
	v_lshrrev_b32_e32 v237, 5, v238
	v_and_b32_e32 v238, 31, v238
	v_add_u32_e32 v239, v239, v238
	v_lshl_add_u32 v240, v239, 10, v240
	v_lshl_add_u32 v240, v242, 6, v240
	v_lshl_add_u32 v240, v237, 5, v240
	v_add_u32_e32 v246, v246, v245
	v_lshlrev_b32_e32 v246, 22, v246
	v_lshl_add_u32 v239, v242, 6, v237
	v_lshlrev_b32_e32 v239, 10, v239
	v_lshl_add_u32 v239, v243, 5, v239
	v_add_u32_e32 v239, v239, v238
	v_lshl_add_u32 v246, v239, 2, v246
	s_nop 0
	v_readfirstlane_b32 s100, v241
	s_nop 4
	s_load_dwordx2 s[100:101], s[0:1], s100
	s_waitcnt lgkmcnt(0)
	global_load_dword v200, v246, s[100:101]
	v_add_u32_e32 v244, 0x2000, v246
	global_load_dword v201, v244, s[100:101]
	v_add_u32_e32 v245, 0x4000, v246
	global_load_dword v202, v245, s[100:101]
	v_add_u32_e32 v244, 0x6000, v246
	global_load_dword v203, v244, s[100:101]
	v_add_u32_e32 v245, 0x8000, v246
	global_load_dword v204, v245, s[100:101]
	v_add_u32_e32 v244, 0xa000, v246
	global_load_dword v205, v244, s[100:101]
	v_add_u32_e32 v245, 0xc000, v246
	global_load_dword v206, v245, s[100:101]
	v_add_u32_e32 v244, 0xe000, v246
	global_load_dword v207, v244, s[100:101]
	v_add_u32_e32 v245, 0x10000, v246
	global_load_dword v208, v245, s[100:101]
	v_add_u32_e32 v244, 0x12000, v246
	global_load_dword v209, v244, s[100:101]
	v_add_u32_e32 v245, 0x14000, v246
	global_load_dword v210, v245, s[100:101]
	v_add_u32_e32 v244, 0x16000, v246
	global_load_dword v211, v244, s[100:101]
	v_add_u32_e32 v245, 0x18000, v246
	global_load_dword v212, v245, s[100:101]
	v_add_u32_e32 v244, 0x1a000, v246
	global_load_dword v213, v244, s[100:101]
	v_add_u32_e32 v245, 0x1c000, v246
	global_load_dword v214, v245, s[100:101]
	v_add_u32_e32 v244, 0x1e000, v246
	global_load_dword v215, v244, s[100:101]
	v_add_u32_e32 v245, 0x20000, v246
	global_load_dword v216, v245, s[100:101]
	v_add_u32_e32 v244, 0x22000, v246
	global_load_dword v217, v244, s[100:101]
	v_add_u32_e32 v245, 0x24000, v246
	global_load_dword v218, v245, s[100:101]
	v_add_u32_e32 v244, 0x26000, v246
	global_load_dword v219, v244, s[100:101]
	v_add_u32_e32 v245, 0x28000, v246
	global_load_dword v220, v245, s[100:101]
	v_add_u32_e32 v244, 0x2a000, v246
	global_load_dword v221, v244, s[100:101]
	v_add_u32_e32 v245, 0x2c000, v246
	global_load_dword v222, v245, s[100:101]
	v_add_u32_e32 v244, 0x2e000, v246
	global_load_dword v223, v244, s[100:101]
	v_add_u32_e32 v245, 0x30000, v246
	global_load_dword v224, v245, s[100:101]
	v_add_u32_e32 v244, 0x32000, v246
	global_load_dword v225, v244, s[100:101]
	v_add_u32_e32 v245, 0x34000, v246
	global_load_dword v226, v245, s[100:101]
	v_add_u32_e32 v244, 0x36000, v246
	global_load_dword v227, v244, s[100:101]
	v_add_u32_e32 v245, 0x38000, v246
	global_load_dword v228, v245, s[100:101]
	v_add_u32_e32 v244, 0x3a000, v246
	global_load_dword v229, v244, s[100:101]
	v_add_u32_e32 v245, 0x3c000, v246
	global_load_dword v230, v245, s[100:101]
	v_add_u32_e32 v244, 0x3e000, v246
	global_load_dword v231, v244, s[100:101]
	s_waitcnt vmcnt(0)
	v_permlane32_swap_b32_e32 v200, v216
	v_permlane32_swap_b32_e32 v201, v217
	v_permlane32_swap_b32_e32 v202, v218
	v_permlane32_swap_b32_e32 v203, v219
	v_permlane32_swap_b32_e32 v204, v220
	v_permlane32_swap_b32_e32 v205, v221
	v_permlane32_swap_b32_e32 v206, v222
	v_permlane32_swap_b32_e32 v207, v223
	v_permlane32_swap_b32_e32 v208, v224
	v_permlane32_swap_b32_e32 v209, v225
	v_permlane32_swap_b32_e32 v210, v226
	v_permlane32_swap_b32_e32 v211, v227
	v_permlane32_swap_b32_e32 v212, v228
	v_permlane32_swap_b32_e32 v213, v229
	v_permlane32_swap_b32_e32 v214, v230
	v_permlane32_swap_b32_e32 v215, v231
	v_mul_f32_e32 v200, 0x42000000, v200
	v_mul_f32_e32 v201, 0x42000000, v201
	v_mul_f32_e32 v202, 0x42000000, v202
	v_mul_f32_e32 v203, 0x42000000, v203
	v_mul_f32_e32 v204, 0x42000000, v204
	v_mul_f32_e32 v205, 0x42000000, v205
	v_mul_f32_e32 v206, 0x42000000, v206
	v_mul_f32_e32 v207, 0x42000000, v207
	v_mul_f32_e32 v208, 0x42000000, v208
	v_mul_f32_e32 v209, 0x42000000, v209
	v_mul_f32_e32 v210, 0x42000000, v210
	v_mul_f32_e32 v211, 0x42000000, v211
	v_mul_f32_e32 v212, 0x42000000, v212
	v_mul_f32_e32 v213, 0x42000000, v213
	v_mul_f32_e32 v214, 0x42000000, v214
	v_mul_f32_e32 v215, 0x42000000, v215
	v_mul_f32_e32 v216, 0x42000000, v216
	v_mul_f32_e32 v217, 0x42000000, v217
	v_mul_f32_e32 v218, 0x42000000, v218
	v_mul_f32_e32 v219, 0x42000000, v219
	v_mul_f32_e32 v220, 0x42000000, v220
	v_mul_f32_e32 v221, 0x42000000, v221
	v_mul_f32_e32 v222, 0x42000000, v222
	v_mul_f32_e32 v223, 0x42000000, v223
	v_mul_f32_e32 v224, 0x42000000, v224
	v_mul_f32_e32 v225, 0x42000000, v225
	v_mul_f32_e32 v226, 0x42000000, v226
	v_mul_f32_e32 v227, 0x42000000, v227
	v_mul_f32_e32 v228, 0x42000000, v228
	v_mul_f32_e32 v229, 0x42000000, v229
	v_mul_f32_e32 v230, 0x42000000, v230
	v_mul_f32_e32 v231, 0x42000000, v231
	v_cvt_pk_fp8_f32 v232, v200, v216
	v_cvt_pk_fp8_f32 v233, v202, v218
	v_cvt_pk_fp8_f32 v234, v204, v220
	v_cvt_pk_fp8_f32 v235, v206, v222
	v_cvt_pk_fp8_f32 v236, v208, v224
	v_cvt_pk_fp8_f32 v237, v210, v226
	v_cvt_pk_fp8_f32 v238, v212, v228
	v_cvt_pk_fp8_f32 v239, v214, v230
	v_cvt_pk_fp8_f32 v232, v201, v217 op_sel:[0,0,1]
	v_cvt_pk_fp8_f32 v233, v203, v219 op_sel:[0,0,1]
	v_cvt_pk_fp8_f32 v234, v205, v221 op_sel:[0,0,1]
	v_cvt_pk_fp8_f32 v235, v207, v223 op_sel:[0,0,1]
	v_cvt_pk_fp8_f32 v236, v209, v225 op_sel:[0,0,1]
	v_cvt_pk_fp8_f32 v237, v211, v227 op_sel:[0,0,1]
	v_cvt_pk_fp8_f32 v238, v213, v229 op_sel:[0,0,1]
	v_cvt_pk_fp8_f32 v239, v215, v231 op_sel:[0,0,1]
	s_nop 0
	global_store_dwordx4 v240, v[232:235], s[52:53]
	global_store_dwordx4 v240, v[236:239], s[52:53] offset:16
.Llc_skip_b:
	s_waitcnt lgkmcnt(0)
	s_barrier
	ds_read_b64 v[30:31], v103
	ds_read_b64 v[32:33], v104 offset:256
	ds_read_b64 v[34:35], v105 offset:512
	ds_read_b64 v[36:37], v106 offset:768
	ds_read_b64 v[38:39], v107 offset:1024
	ds_read_b64 v[40:41], v108 offset:1280
	ds_read_b64 v[42:43], v109 offset:1536
	ds_read_b64 v[44:45], v110 offset:1792
	ds_read_b64 v[46:47], v111 offset:2048
	ds_read_b64 v[48:49], v112 offset:2304
	ds_read_b64 v[50:51], v113 offset:2560
	ds_read_b64 v[52:53], v114 offset:2816
	ds_read_b64 v[54:55], v27
	ds_read_b64 v[56:57], v115 offset:3072
	ds_read_b64 v[58:59], v116 offset:3328
	ds_read_b64 v[60:61], v117 offset:3584
	ds_read_b64 v[62:63], v118 offset:3840
	s_waitcnt lgkmcnt(4)
	v_pk_mul_f32 v[64:65], v[54:55], v[54:55] op_sel:[0,1]
	s_mov_b32 s29, s22
	v_pk_fma_f32 v[66:67], v[54:55], v[54:55], v[64:65] op_sel:[0,0,1] op_sel_hi:[0,1,0] neg_lo:[0,0,1] neg_hi:[0,0,1]
	v_pk_fma_f32 v[64:65], v[54:55], v[54:55], v[64:65] op_sel:[0,0,1] op_sel_hi:[0,1,0]
	v_pk_mov_b32 v[70:71], v[64:65], v[66:67] op_sel:[1,0]
	v_pk_mul_f32 v[74:75], v[54:55], v[64:65] op_sel:[0,1]
	v_mov_b32_e32 v68, v66
	v_mov_b32_e32 v69, v65
	v_pk_mul_f32 v[70:71], v[64:65], v[70:71] op_sel:[1,0]
	v_pk_fma_f32 v[76:77], v[54:55], v[66:67], v[74:75] op_sel:[0,0,1] op_sel_hi:[1,0,0] neg_lo:[0,0,1] neg_hi:[0,0,1]
	v_pk_fma_f32 v[74:75], v[54:55], v[66:67], v[74:75] op_sel:[0,0,1] op_sel_hi:[1,0,0]
	v_pk_fma_f32 v[72:73], v[66:67], v[68:69], v[70:71] op_sel_hi:[0,1,1] neg_lo:[0,0,1] neg_hi:[0,0,1]
	v_pk_fma_f32 v[68:69], v[66:67], v[68:69], v[70:71] op_sel_hi:[0,1,1]
	v_mov_b32_e32 v78, v76
	v_mov_b32_e32 v79, v75
	v_pk_mul_f32 v[80:81], v[78:79], v[78:79]
	v_pk_mul_f32 v[78:79], v[78:79], v[74:75] op_sel:[0,1] op_sel_hi:[1,0]
	v_pk_mov_b32 v[82:83], v[68:69], v[72:73] op_sel:[1,0]
	v_mov_b32_e32 v70, v72
	v_mov_b32_e32 v71, v69
	v_pk_mul_f32 v[82:83], v[68:69], v[82:83] op_sel:[1,0]
	v_mov_b32_e32 v174, v80
	v_mov_b32_e32 v175, v78
	v_pk_mov_b32 v[78:79], v[80:81], v[78:79] op_sel:[1,0]
	v_pk_fma_f32 v[84:85], v[72:73], v[70:71], v[82:83] op_sel_hi:[0,1,1] neg_lo:[0,0,1] neg_hi:[0,0,1]
	v_pk_fma_f32 v[70:71], v[72:73], v[70:71], v[82:83] op_sel_hi:[0,1,1]
	v_pk_add_f32 v[80:81], v[174:175], v[78:79] neg_lo:[0,1] neg_hi:[0,1]
	v_pk_add_f32 v[78:79], v[174:175], v[78:79]
	v_mov_b32_e32 v83, v71
	v_mov_b32_e32 v174, v80
	v_mov_b32_e32 v175, v79
	v_pk_mul_f32 v[70:71], v[32:33], v[70:71] op_sel:[1,1] op_sel_hi:[0,1]
	v_pk_mul_f32 v[176:177], v[174:175], v[174:175]
	v_pk_mul_f32 v[174:175], v[174:175], v[78:79] op_sel:[0,1] op_sel_hi:[1,0]
	v_pk_fma_f32 v[194:195], v[32:33], v[84:85], v[70:71]
	v_pk_fma_f32 v[32:33], v[32:33], v[84:85], v[70:71] op_sel_hi:[1,0,1] neg_lo:[0,0,1] neg_hi:[0,0,1]
	v_pk_mul_f32 v[88:89], v[54:55], v[68:69] op_sel:[0,1]
	v_mov_b32_e32 v178, v176
	v_mov_b32_e32 v179, v174
	v_pk_mov_b32 v[174:175], v[176:177], v[174:175] op_sel:[1,0]
	v_mov_b32_e32 v195, v33
	v_pk_mul_f32 v[32:33], v[34:35], v[68:69] op_sel:[1,1] op_sel_hi:[0,1]
	v_pk_fma_f32 v[90:91], v[54:55], v[72:73], v[88:89] op_sel:[0,0,1] op_sel_hi:[1,0,0] neg_lo:[0,0,1] neg_hi:[0,0,1]
	v_pk_fma_f32 v[88:89], v[54:55], v[72:73], v[88:89] op_sel:[0,0,1] op_sel_hi:[1,0,0]
	v_pk_add_f32 v[176:177], v[178:179], v[174:175] neg_lo:[0,1] neg_hi:[0,1]
	v_pk_add_f32 v[174:175], v[178:179], v[174:175]
	v_pk_fma_f32 v[68:69], v[34:35], v[72:73], v[32:33]
	v_pk_fma_f32 v[32:33], v[34:35], v[72:73], v[32:33] op_sel_hi:[1,0,1] neg_lo:[0,0,1] neg_hi:[0,0,1]
	v_mov_b32_e32 v92, v90
	v_mov_b32_e32 v93, v89
	v_mov_b32_e32 v69, v33
	v_pk_mul_f32 v[32:33], v[36:37], v[174:175] op_sel:[1,1] op_sel_hi:[0,1]
	v_pk_mul_f32 v[94:95], v[92:93], v[92:93]
	v_pk_mul_f32 v[92:93], v[92:93], v[88:89] op_sel:[0,1] op_sel_hi:[1,0]
	v_pk_fma_f32 v[34:35], v[36:37], v[176:177], v[32:33]
	v_pk_fma_f32 v[32:33], v[36:37], v[176:177], v[32:33] op_sel_hi:[1,0,1] neg_lo:[0,0,1] neg_hi:[0,0,1]
	v_mov_b32_e32 v170, v94
	v_mov_b32_e32 v171, v92
	v_pk_mov_b32 v[92:93], v[94:95], v[92:93] op_sel:[1,0]
	v_pk_mul_f32 v[182:183], v[54:55], v[78:79] op_sel:[0,1]
	v_mov_b32_e32 v35, v33
	v_pk_mul_f32 v[32:33], v[38:39], v[64:65] op_sel:[1,1] op_sel_hi:[0,1]
	v_pk_add_f32 v[94:95], v[170:171], v[92:93] neg_lo:[0,1] neg_hi:[0,1]
	v_pk_add_f32 v[92:93], v[170:171], v[92:93]
	v_pk_fma_f32 v[184:185], v[54:55], v[80:81], v[182:183] op_sel:[0,0,1] op_sel_hi:[1,0,0] neg_lo:[0,0,1] neg_hi:[0,0,1]
	v_pk_fma_f32 v[182:183], v[54:55], v[80:81], v[182:183] op_sel:[0,0,1] op_sel_hi:[1,0,0]
	v_pk_fma_f32 v[36:37], v[38:39], v[66:67], v[32:33]
	v_pk_fma_f32 v[32:33], v[38:39], v[66:67], v[32:33] op_sel_hi:[1,0,1] neg_lo:[0,0,1] neg_hi:[0,0,1]
	v_mov_b32_e32 v186, v184
	v_mov_b32_e32 v187, v183
	v_mov_b32_e32 v37, v33
	v_pk_mul_f32 v[32:33], v[40:41], v[92:93] op_sel:[1,1] op_sel_hi:[0,1]
	v_pk_mul_f32 v[188:189], v[186:187], v[186:187]
	v_pk_mul_f32 v[186:187], v[186:187], v[182:183] op_sel:[0,1] op_sel_hi:[1,0]
	v_pk_fma_f32 v[38:39], v[40:41], v[94:95], v[32:33]
	v_pk_fma_f32 v[32:33], v[40:41], v[94:95], v[32:33] op_sel_hi:[1,0,1] neg_lo:[0,0,1] neg_hi:[0,0,1]
	v_mov_b32_e32 v190, v188
	v_mov_b32_e32 v191, v186
	v_pk_mov_b32 v[186:187], v[188:189], v[186:187] op_sel:[1,0]
	v_mov_b32_e32 v39, v33
	v_pk_mul_f32 v[32:33], v[42:43], v[78:79] op_sel:[0,1]
	v_pk_add_f32 v[188:189], v[190:191], v[186:187] neg_lo:[0,1] neg_hi:[0,1]
	v_pk_add_f32 v[186:187], v[190:191], v[186:187]
	v_pk_fma_f32 v[40:41], v[42:43], v[80:81], v[32:33] op_sel:[0,0,1] op_sel_hi:[1,1,0]
	v_pk_fma_f32 v[32:33], v[42:43], v[80:81], v[32:33] op_sel:[0,0,1] op_sel_hi:[1,0,0] neg_lo:[0,0,1] neg_hi:[0,0,1]
	v_mov_b32_e32 v82, v84
	v_mov_b32_e32 v41, v33
	v_pk_mul_f32 v[32:33], v[44:45], v[186:187] op_sel:[1,1] op_sel_hi:[0,1]
	v_pk_fma_f32 v[42:43], v[44:45], v[188:189], v[32:33]
	v_pk_fma_f32 v[32:33], v[44:45], v[188:189], v[32:33] op_sel_hi:[1,0,1] neg_lo:[0,0,1] neg_hi:[0,0,1]
	v_pk_mul_f32 v[86:87], v[54:55], v[82:83]
	v_pk_mul_f32 v[82:83], v[54:55], v[82:83] op_sel:[1,0] op_sel_hi:[0,1]
	v_mov_b32_e32 v43, v33
	v_pk_mul_f32 v[32:33], v[46:47], v[54:55] op_sel:[0,1]
	v_mov_b32_e32 v170, v94
	v_pk_fma_f32 v[44:45], v[46:47], v[54:55], v[32:33] op_sel:[0,0,1] op_sel_hi:[1,1,0]
	v_pk_fma_f32 v[32:33], v[46:47], v[54:55], v[32:33] op_sel:[0,0,1] op_sel_hi:[1,0,0] neg_lo:[0,0,1] neg_hi:[0,0,1]
	v_pk_add_f32 v[46:47], v[82:83], v[82:83] op_sel:[0,1] op_sel_hi:[0,1]
	v_mov_b32_e32 v171, v93
	v_mov_b32_e32 v178, v176
	v_mov_b32_e32 v179, v175
	v_mov_b32_e32 v190, v188
	v_mov_b32_e32 v191, v187
	v_mov_b32_e32 v45, v33
	v_pk_add_f32 v[32:33], v[86:87], v[86:87] op_sel:[0,1] op_sel_hi:[0,1] neg_lo:[0,1] neg_hi:[0,1]
	v_pk_mul_f32 v[46:47], v[48:49], v[46:47] op_sel:[1,0] op_sel_hi:[0,1]
	v_pk_mul_f32 v[172:173], v[54:55], v[170:171]
	v_pk_mul_f32 v[170:171], v[54:55], v[170:171] op_sel:[1,0] op_sel_hi:[0,1]
	v_pk_mul_f32 v[180:181], v[54:55], v[178:179]
	v_pk_mul_f32 v[178:179], v[54:55], v[178:179] op_sel:[1,0] op_sel_hi:[0,1]
	v_pk_mul_f32 v[192:193], v[54:55], v[190:191]
	v_pk_mul_f32 v[190:191], v[54:55], v[190:191] op_sel:[1,0] op_sel_hi:[0,1]
	v_pk_fma_f32 v[54:55], v[48:49], v[32:33], v[46:47]
	v_pk_fma_f32 v[32:33], v[48:49], v[32:33], v[46:47] neg_lo:[0,0,1] neg_hi:[0,0,1]
	v_pk_add_f32 v[48:49], v[178:179], v[178:179] op_sel:[0,1] op_sel_hi:[0,1]
	v_mov_b32_e32 v55, v33
	v_pk_mul_f32 v[32:33], v[50:51], v[88:89] op_sel:[1,1] op_sel_hi:[0,1]
	v_pk_fma_f32 v[46:47], v[50:51], v[90:91], v[32:33]
	v_pk_fma_f32 v[32:33], v[50:51], v[90:91], v[32:33] op_sel_hi:[1,0,1] neg_lo:[0,0,1] neg_hi:[0,0,1]
	v_pk_mul_f32 v[48:49], v[52:53], v[48:49] op_sel:[1,0] op_sel_hi:[0,1]
	v_mov_b32_e32 v47, v33
	v_pk_add_f32 v[32:33], v[180:181], v[180:181] op_sel:[0,1] op_sel_hi:[0,1] neg_lo:[0,1] neg_hi:[0,1]
	v_pk_fma_f32 v[50:51], v[52:53], v[32:33], v[48:49]
	v_pk_fma_f32 v[32:33], v[52:53], v[32:33], v[48:49] neg_lo:[0,0,1] neg_hi:[0,0,1]
	v_pk_add_f32 v[52:53], v[170:171], v[170:171] op_sel:[0,1] op_sel_hi:[0,1]
	v_mov_b32_e32 v51, v33
	s_waitcnt lgkmcnt(3)
	v_pk_mul_f32 v[32:33], v[56:57], v[74:75] op_sel:[1,1] op_sel_hi:[0,1]
	v_pk_fma_f32 v[48:49], v[56:57], v[76:77], v[32:33]
	v_pk_fma_f32 v[32:33], v[56:57], v[76:77], v[32:33] op_sel_hi:[1,0,1] neg_lo:[0,0,1] neg_hi:[0,0,1]
	s_waitcnt lgkmcnt(2)
	v_pk_mul_f32 v[52:53], v[58:59], v[52:53] op_sel:[1,0] op_sel_hi:[0,1]
	v_mov_b32_e32 v49, v33
	v_pk_add_f32 v[32:33], v[172:173], v[172:173] op_sel:[0,1] op_sel_hi:[0,1] neg_lo:[0,1] neg_hi:[0,1]
	v_pk_fma_f32 v[56:57], v[58:59], v[32:33], v[52:53]
	v_pk_fma_f32 v[32:33], v[58:59], v[32:33], v[52:53] neg_lo:[0,0,1] neg_hi:[0,0,1]
	v_pk_add_f32 v[58:59], v[190:191], v[190:191] op_sel:[0,1] op_sel_hi:[0,1]
	v_mov_b32_e32 v57, v33
	s_waitcnt lgkmcnt(1)
	v_pk_mul_f32 v[32:33], v[60:61], v[182:183] op_sel:[1,1] op_sel_hi:[0,1]
	v_pk_fma_f32 v[52:53], v[60:61], v[184:185], v[32:33]
	v_pk_fma_f32 v[32:33], v[60:61], v[184:185], v[32:33] op_sel_hi:[1,0,1] neg_lo:[0,0,1] neg_hi:[0,0,1]
	s_waitcnt lgkmcnt(0)
	v_pk_mul_f32 v[58:59], v[62:63], v[58:59] op_sel:[1,0] op_sel_hi:[0,1]
	v_mov_b32_e32 v53, v33
	v_pk_add_f32 v[32:33], v[192:193], v[192:193] op_sel:[0,1] op_sel_hi:[0,1] neg_lo:[0,1] neg_hi:[0,1]
	v_pk_fma_f32 v[60:61], v[62:63], v[32:33], v[58:59]
	v_pk_fma_f32 v[32:33], v[62:63], v[32:33], v[58:59] neg_lo:[0,0,1] neg_hi:[0,0,1]
	v_pk_add_f32 v[58:59], v[68:69], v[34:35]
	v_mov_b32_e32 v61, v33
	v_pk_add_f32 v[32:33], v[30:31], v[194:195]
	v_pk_add_f32 v[34:35], v[68:69], v[34:35] neg_lo:[0,1] neg_hi:[0,1]
	v_pk_add_f32 v[30:31], v[30:31], v[194:195] neg_lo:[0,1] neg_hi:[0,1]
	v_pk_add_f32 v[62:63], v[36:37], v[38:39]
	v_pk_add_f32 v[36:37], v[36:37], v[38:39] neg_lo:[0,1] neg_hi:[0,1]
	v_pk_add_f32 v[38:39], v[40:41], v[42:43]
	v_pk_add_f32 v[40:41], v[40:41], v[42:43] neg_lo:[0,1] neg_hi:[0,1]
	v_pk_add_f32 v[42:43], v[44:45], v[54:55]
	v_pk_add_f32 v[44:45], v[44:45], v[54:55] neg_lo:[0,1] neg_hi:[0,1]
	v_pk_add_f32 v[54:55], v[46:47], v[50:51]
	v_pk_add_f32 v[46:47], v[46:47], v[50:51] neg_lo:[0,1] neg_hi:[0,1]
	v_pk_add_f32 v[50:51], v[48:49], v[56:57]
	v_pk_add_f32 v[48:49], v[48:49], v[56:57] neg_lo:[0,1] neg_hi:[0,1]
	v_pk_add_f32 v[56:57], v[52:53], v[60:61]
	v_pk_add_f32 v[52:53], v[52:53], v[60:61] neg_lo:[0,1] neg_hi:[0,1]
	v_pk_add_f32 v[60:61], v[32:33], v[58:59]
	v_pk_add_f32 v[32:33], v[32:33], v[58:59] neg_lo:[0,1] neg_hi:[0,1]
	v_xor_b32_e32 v58, 0x80000000, v35
	v_mov_b32_e32 v59, v34
	v_pk_add_f32 v[34:35], v[30:31], v[58:59]
	v_pk_add_f32 v[30:31], v[30:31], v[58:59] neg_lo:[0,1] neg_hi:[0,1]
	v_pk_add_f32 v[58:59], v[62:63], v[38:39]
	v_pk_add_f32 v[38:39], v[62:63], v[38:39] neg_lo:[0,1] neg_hi:[0,1]
	v_xor_b32_e32 v62, 0x80000000, v41
	v_mov_b32_e32 v63, v40
	v_pk_add_f32 v[40:41], v[36:37], v[62:63]
	v_pk_add_f32 v[36:37], v[36:37], v[62:63] neg_lo:[0,1] neg_hi:[0,1]
	v_pk_add_f32 v[62:63], v[42:43], v[54:55]
	v_pk_add_f32 v[42:43], v[42:43], v[54:55] neg_lo:[0,1] neg_hi:[0,1]
	v_xor_b32_e32 v54, 0x80000000, v47
	v_mov_b32_e32 v55, v46
	v_pk_add_f32 v[46:47], v[44:45], v[54:55]
	v_pk_add_f32 v[44:45], v[44:45], v[54:55] neg_lo:[0,1] neg_hi:[0,1]
	v_pk_add_f32 v[54:55], v[50:51], v[56:57]
	v_pk_add_f32 v[50:51], v[50:51], v[56:57] neg_lo:[0,1] neg_hi:[0,1]
	v_xor_b32_e32 v56, 0x80000000, v53
	v_mov_b32_e32 v57, v52
	v_pk_add_f32 v[52:53], v[48:49], v[56:57]
	v_pk_add_f32 v[48:49], v[48:49], v[56:57] neg_lo:[0,1] neg_hi:[0,1]
	v_pk_add_f32 v[56:57], v[60:61], v[58:59]
	v_pk_add_f32 v[58:59], v[60:61], v[58:59] neg_lo:[0,1] neg_hi:[0,1]
	v_pk_mul_f32 v[60:61], v[40:41], s[22:23] op_sel_hi:[1,0]
	s_mov_b32 s31, s18
	v_pk_fma_f32 v[64:65], v[40:41], s[22:23], v[60:61] op_sel:[0,0,1] op_sel_hi:[1,0,0] neg_lo:[0,0,1] neg_hi:[0,0,1]
	v_pk_fma_f32 v[40:41], v[40:41], s[22:23], v[60:61] op_sel_hi:[1,0,0]
	v_xor_b32_e32 v60, 0x80000000, v39
	v_mov_b32_e32 v61, v38
	v_pk_add_f32 v[38:39], v[32:33], v[60:61]
	v_pk_add_f32 v[32:33], v[32:33], v[60:61] neg_lo:[0,1] neg_hi:[0,1]
	v_mul_f32_e32 v60, 0x3f3504f3, v37
	v_pk_fma_f32 v[36:37], v[36:37], s[28:29], v[60:61] op_sel_hi:[0,1,0] neg_lo:[0,0,1] neg_hi:[0,0,1]
	v_mov_b32_e32 v65, v41
	v_pk_add_f32 v[60:61], v[30:31], v[36:37]
	v_pk_add_f32 v[30:31], v[30:31], v[36:37] neg_lo:[0,1] neg_hi:[0,1]
	v_pk_add_f32 v[36:37], v[62:63], v[54:55]
	v_pk_add_f32 v[54:55], v[62:63], v[54:55] neg_lo:[0,1] neg_hi:[0,1]
	v_pk_mul_f32 v[62:63], v[52:53], s[22:23] op_sel_hi:[1,0]
	v_pk_add_f32 v[40:41], v[34:35], v[64:65]
	v_pk_add_f32 v[34:35], v[34:35], v[64:65] neg_lo:[0,1] neg_hi:[0,1]
	v_pk_fma_f32 v[64:65], v[52:53], s[22:23], v[62:63] op_sel:[0,0,1] op_sel_hi:[1,0,0] neg_lo:[0,0,1] neg_hi:[0,0,1]
	v_pk_fma_f32 v[52:53], v[52:53], s[22:23], v[62:63] op_sel_hi:[1,0,0]
	v_xor_b32_e32 v62, 0x80000000, v51
	v_mov_b32_e32 v63, v50
	v_mov_b32_e32 v65, v53
	v_pk_add_f32 v[50:51], v[42:43], v[62:63]
	v_pk_add_f32 v[42:43], v[42:43], v[62:63] neg_lo:[0,1] neg_hi:[0,1]
	v_mul_f32_e32 v62, 0x3f3504f3, v49
	v_pk_add_f32 v[52:53], v[46:47], v[64:65]
	v_pk_fma_f32 v[48:49], v[48:49], s[28:29], v[62:63] op_sel_hi:[0,1,0] neg_lo:[0,0,1] neg_hi:[0,0,1]
	v_pk_add_f32 v[62:63], v[44:45], v[48:49]
	v_pk_add_f32 v[44:45], v[44:45], v[48:49] neg_lo:[0,1] neg_hi:[0,1]
	v_pk_add_f32 v[48:49], v[56:57], v[36:37]
	v_pk_add_f32 v[36:37], v[56:57], v[36:37] neg_lo:[0,1] neg_hi:[0,1]
	v_pk_mul_f32 v[56:57], v[52:53], s[16:17] op_sel_hi:[1,0]
	v_pk_add_f32 v[46:47], v[46:47], v[64:65] neg_lo:[0,1] neg_hi:[0,1]
	v_pk_fma_f32 v[64:65], v[52:53], s[18:19], v[56:57] op_sel:[0,0,1] op_sel_hi:[1,0,0] neg_lo:[0,0,1] neg_hi:[0,0,1]
	v_pk_fma_f32 v[52:53], v[52:53], s[18:19], v[56:57] op_sel:[0,0,1] op_sel_hi:[1,0,0]
	v_pk_mul_f32 v[56:57], v[50:51], s[22:23] op_sel_hi:[1,0]
	v_mov_b32_e32 v65, v53
	v_pk_add_f32 v[52:53], v[40:41], v[64:65]
	v_pk_add_f32 v[40:41], v[40:41], v[64:65] neg_lo:[0,1] neg_hi:[0,1]
	v_pk_fma_f32 v[64:65], v[50:51], s[22:23], v[56:57] op_sel:[0,0,1] op_sel_hi:[1,0,0] neg_lo:[0,0,1] neg_hi:[0,0,1]
	v_pk_fma_f32 v[50:51], v[50:51], s[22:23], v[56:57] op_sel_hi:[1,0,0]
	v_pk_mul_f32 v[56:57], v[62:63], s[18:19] op_sel_hi:[1,0]
	v_mov_b32_e32 v65, v51
	v_pk_add_f32 v[50:51], v[38:39], v[64:65]
	v_pk_add_f32 v[38:39], v[38:39], v[64:65] neg_lo:[0,1] neg_hi:[0,1]
	v_pk_fma_f32 v[64:65], v[62:63], s[16:17], v[56:57] op_sel:[0,0,1] op_sel_hi:[1,0,0] neg_lo:[0,0,1] neg_hi:[0,0,1]
	v_pk_fma_f32 v[56:57], v[62:63], s[16:17], v[56:57] op_sel:[0,0,1] op_sel_hi:[1,0,0]
	v_xor_b32_e32 v62, 0x80000000, v55
	v_mov_b32_e32 v63, v54
	s_mov_b32 s19, s16
	v_pk_add_f32 v[54:55], v[58:59], v[62:63]
	v_pk_add_f32 v[58:59], v[58:59], v[62:63] neg_lo:[0,1] neg_hi:[0,1]
	v_pk_mul_f32 v[62:63], v[46:47], s[18:19] op_sel:[1,0]
	s_mov_b32 s17, s18
	v_pk_fma_f32 v[46:47], v[46:47], s[30:31], v[62:63] op_sel_hi:[0,1,1] neg_lo:[0,0,1] neg_hi:[0,0,1]
	v_pk_add_f32 v[62:63], v[34:35], v[46:47]
	v_pk_add_f32 v[34:35], v[34:35], v[46:47] neg_lo:[0,1] neg_hi:[0,1]
	v_mul_f32_e32 v46, 0x3f3504f3, v43
	v_pk_fma_f32 v[42:43], v[42:43], s[28:29], v[46:47] op_sel_hi:[0,1,0] neg_lo:[0,0,1] neg_hi:[0,0,1]
	v_pk_add_f32 v[46:47], v[32:33], v[42:43]
	v_pk_add_f32 v[32:33], v[32:33], v[42:43] neg_lo:[0,1] neg_hi:[0,1]
	s_mov_b32 s25, s16
	v_pk_mul_f32 v[42:43], v[44:45], s[16:17] op_sel:[1,0]
	v_mov_b32_e32 v65, v57
	v_pk_fma_f32 v[42:43], v[44:45], s[24:25], v[42:43] op_sel_hi:[0,1,1] neg_lo:[0,0,1] neg_hi:[0,0,1]
	v_pk_add_f32 v[56:57], v[60:61], v[64:65]
	v_pk_add_f32 v[60:61], v[60:61], v[64:65] neg_lo:[0,1] neg_hi:[0,1]
	v_pk_add_f32 v[44:45], v[30:31], v[42:43]
	v_pk_add_f32 v[30:31], v[30:31], v[42:43] neg_lo:[0,1] neg_hi:[0,1]
	ds_write_b64 v103, v[48:49]
	ds_write_b64 v104, v[52:53] offset:256
	ds_write_b64 v105, v[50:51] offset:512
	ds_write_b64 v106, v[56:57] offset:768
	ds_write_b64 v107, v[54:55] offset:1024
	ds_write_b64 v108, v[62:63] offset:1280
	ds_write_b64 v109, v[46:47] offset:1536
	ds_write_b64 v110, v[44:45] offset:1792
	ds_write_b64 v111, v[36:37] offset:2048
	ds_write_b64 v112, v[40:41] offset:2304
	ds_write_b64 v113, v[38:39] offset:2560
	ds_write_b64 v114, v[60:61] offset:2816
	ds_write_b64 v115, v[58:59] offset:3072
	ds_write_b64 v116, v[34:35] offset:3328
	ds_write_b64 v117, v[32:33] offset:3584
	ds_write_b64 v118, v[30:31] offset:3840
	s_waitcnt lgkmcnt(0)
	s_barrier
	ds_read_b64 v[30:31], v122 offset:12288
	ds_read_b64 v[32:33], v123 offset:16384
	ds_read_b64 v[34:35], v124 offset:20480
	ds_read_b64 v[36:37], v125 offset:24576
	ds_read_b64 v[38:39], v126 offset:28672
	ds_read_b64 v[40:41], v127 offset:32768
	ds_read_b64 v[42:43], v128 offset:36864
	ds_read_b64 v[44:45], v129 offset:40960
	ds_read_b64 v[46:47], v119
	ds_read_b64 v[48:49], v120 offset:4096
	ds_read_b64 v[50:51], v121 offset:8192
	ds_read_b64 v[52:53], v102
	ds_read_b64 v[54:55], v130 offset:45056
	ds_read_b64 v[56:57], v131 offset:49152
	ds_read_b64 v[58:59], v132 offset:53248
	ds_read_b64 v[60:61], v133 offset:57344
	ds_read_b64 v[62:63], v134 offset:61440
	s_waitcnt lgkmcnt(5)
	v_xor_b32_e32 v64, 0x80000000, v52
	v_cndmask_b32_e64 v65, v64, v53, s[10:11]
	v_cndmask_b32_e64 v64, v53, v52, s[10:11]
	v_mov_b32_e32 v52, v65
	v_pk_mul_f32 v[66:67], v[64:65], v[52:53] op_sel_hi:[1,0]
	s_addk_i32 s78, 0x800
	v_pk_fma_f32 v[68:69], v[64:65], v[64:65], v[66:67] op_sel:[0,0,1] op_sel_hi:[0,1,0] neg_lo:[0,0,1] neg_hi:[0,0,1]
	v_pk_fma_f32 v[66:67], v[64:65], v[64:65], v[66:67] op_sel:[0,0,1] op_sel_hi:[0,1,0]
	v_pk_mov_b32 v[72:73], v[66:67], v[68:69] op_sel:[1,0]
	v_pk_mul_f32 v[76:77], v[64:65], v[66:67] op_sel:[0,1]
	v_mov_b32_e32 v70, v68
	v_mov_b32_e32 v71, v67
	v_pk_mul_f32 v[72:73], v[66:67], v[72:73] op_sel:[1,0]
	v_pk_fma_f32 v[78:79], v[64:65], v[68:69], v[76:77] op_sel:[0,0,1] op_sel_hi:[1,0,0] neg_lo:[0,0,1] neg_hi:[0,0,1]
	v_pk_fma_f32 v[76:77], v[64:65], v[68:69], v[76:77] op_sel:[0,0,1] op_sel_hi:[1,0,0]
	v_pk_fma_f32 v[74:75], v[68:69], v[70:71], v[72:73] op_sel_hi:[0,1,1] neg_lo:[0,0,1] neg_hi:[0,0,1]
	v_pk_fma_f32 v[70:71], v[68:69], v[70:71], v[72:73] op_sel_hi:[0,1,1]
	v_mov_b32_e32 v80, v78
	v_mov_b32_e32 v81, v77
	v_pk_mul_f32 v[82:83], v[80:81], v[80:81]
	v_pk_mul_f32 v[80:81], v[80:81], v[76:77] op_sel:[0,1] op_sel_hi:[1,0]
	v_pk_mov_b32 v[84:85], v[70:71], v[74:75] op_sel:[1,0]
	v_mov_b32_e32 v72, v74
	v_mov_b32_e32 v73, v71
	v_pk_mul_f32 v[84:85], v[70:71], v[84:85] op_sel:[1,0]
	v_mov_b32_e32 v176, v82
	v_mov_b32_e32 v177, v80
	v_pk_mov_b32 v[80:81], v[82:83], v[80:81] op_sel:[1,0]
	v_pk_fma_f32 v[86:87], v[74:75], v[72:73], v[84:85] op_sel_hi:[0,1,1] neg_lo:[0,0,1] neg_hi:[0,0,1]
	v_pk_fma_f32 v[72:73], v[74:75], v[72:73], v[84:85] op_sel_hi:[0,1,1]
	v_pk_add_f32 v[82:83], v[176:177], v[80:81] neg_lo:[0,1] neg_hi:[0,1]
	v_pk_add_f32 v[80:81], v[176:177], v[80:81]
	v_mov_b32_e32 v85, v73
	v_mov_b32_e32 v176, v82
	v_mov_b32_e32 v177, v81
	v_pk_mul_f32 v[72:73], v[48:49], v[72:73] op_sel:[1,1] op_sel_hi:[0,1]
	v_pk_mul_f32 v[178:179], v[176:177], v[176:177]
	v_pk_mul_f32 v[176:177], v[176:177], v[80:81] op_sel:[0,1] op_sel_hi:[1,0]
	v_pk_fma_f32 v[196:197], v[48:49], v[86:87], v[72:73]
	v_pk_fma_f32 v[48:49], v[48:49], v[86:87], v[72:73] op_sel_hi:[1,0,1] neg_lo:[0,0,1] neg_hi:[0,0,1]
	v_pk_mul_f32 v[90:91], v[64:65], v[70:71] op_sel:[0,1]
	v_mov_b32_e32 v180, v178
	v_mov_b32_e32 v181, v176
	v_pk_mov_b32 v[176:177], v[178:179], v[176:177] op_sel:[1,0]
	v_mov_b32_e32 v197, v49
	v_pk_mul_f32 v[48:49], v[50:51], v[70:71] op_sel:[1,1] op_sel_hi:[0,1]
	v_pk_fma_f32 v[92:93], v[64:65], v[74:75], v[90:91] op_sel:[0,0,1] op_sel_hi:[1,0,0] neg_lo:[0,0,1] neg_hi:[0,0,1]
	v_pk_fma_f32 v[90:91], v[64:65], v[74:75], v[90:91] op_sel:[0,0,1] op_sel_hi:[1,0,0]
	v_pk_add_f32 v[178:179], v[180:181], v[176:177] neg_lo:[0,1] neg_hi:[0,1]
	v_pk_add_f32 v[176:177], v[180:181], v[176:177]
	v_pk_fma_f32 v[70:71], v[50:51], v[74:75], v[48:49]
	v_pk_fma_f32 v[48:49], v[50:51], v[74:75], v[48:49] op_sel_hi:[1,0,1] neg_lo:[0,0,1] neg_hi:[0,0,1]
	v_mov_b32_e32 v94, v92
	v_mov_b32_e32 v95, v91
	v_mov_b32_e32 v71, v49
	v_pk_mul_f32 v[48:49], v[30:31], v[176:177] op_sel:[1,1] op_sel_hi:[0,1]
	v_pk_mul_f32 v[170:171], v[94:95], v[94:95]
	v_pk_mul_f32 v[94:95], v[94:95], v[90:91] op_sel:[0,1] op_sel_hi:[1,0]
	v_pk_fma_f32 v[50:51], v[30:31], v[178:179], v[48:49]
	v_pk_fma_f32 v[30:31], v[30:31], v[178:179], v[48:49] op_sel_hi:[1,0,1] neg_lo:[0,0,1] neg_hi:[0,0,1]
	v_mov_b32_e32 v172, v170
	v_mov_b32_e32 v173, v94
	v_pk_mov_b32 v[94:95], v[170:171], v[94:95] op_sel:[1,0]
	v_pk_mul_f32 v[184:185], v[64:65], v[80:81] op_sel:[0,1]
	v_mov_b32_e32 v51, v31
	v_pk_mul_f32 v[30:31], v[32:33], v[66:67] op_sel:[1,1] op_sel_hi:[0,1]
	v_pk_add_f32 v[170:171], v[172:173], v[94:95] neg_lo:[0,1] neg_hi:[0,1]
	v_pk_add_f32 v[94:95], v[172:173], v[94:95]
	v_pk_fma_f32 v[186:187], v[64:65], v[82:83], v[184:185] op_sel:[0,0,1] op_sel_hi:[1,0,0] neg_lo:[0,0,1] neg_hi:[0,0,1]
	v_pk_fma_f32 v[184:185], v[64:65], v[82:83], v[184:185] op_sel:[0,0,1] op_sel_hi:[1,0,0]
	v_pk_fma_f32 v[48:49], v[32:33], v[68:69], v[30:31]
	v_pk_fma_f32 v[30:31], v[32:33], v[68:69], v[30:31] op_sel_hi:[1,0,1] neg_lo:[0,0,1] neg_hi:[0,0,1]
	v_mov_b32_e32 v188, v186
	v_mov_b32_e32 v189, v185
	v_mov_b32_e32 v49, v31
	v_pk_mul_f32 v[30:31], v[34:35], v[94:95] op_sel:[1,1] op_sel_hi:[0,1]
	v_pk_mul_f32 v[190:191], v[188:189], v[188:189]
	v_pk_mul_f32 v[188:189], v[188:189], v[184:185] op_sel:[0,1] op_sel_hi:[1,0]
	v_pk_fma_f32 v[32:33], v[34:35], v[170:171], v[30:31]
	v_pk_fma_f32 v[30:31], v[34:35], v[170:171], v[30:31] op_sel_hi:[1,0,1] neg_lo:[0,0,1] neg_hi:[0,0,1]
	v_mov_b32_e32 v192, v190
	v_mov_b32_e32 v193, v188
	v_pk_mov_b32 v[188:189], v[190:191], v[188:189] op_sel:[1,0]
	v_mov_b32_e32 v33, v31
	v_pk_mul_f32 v[30:31], v[36:37], v[80:81] op_sel:[0,1]
	v_pk_add_f32 v[190:191], v[192:193], v[188:189] neg_lo:[0,1] neg_hi:[0,1]
	v_pk_add_f32 v[188:189], v[192:193], v[188:189]
	v_pk_fma_f32 v[34:35], v[36:37], v[82:83], v[30:31] op_sel:[0,0,1] op_sel_hi:[1,1,0]
	v_pk_fma_f32 v[30:31], v[36:37], v[82:83], v[30:31] op_sel:[0,0,1] op_sel_hi:[1,0,0] neg_lo:[0,0,1] neg_hi:[0,0,1]
	v_mov_b32_e32 v84, v86
	v_mov_b32_e32 v35, v31
	v_pk_mul_f32 v[30:31], v[38:39], v[188:189] op_sel:[1,1] op_sel_hi:[0,1]
	v_pk_fma_f32 v[36:37], v[38:39], v[190:191], v[30:31]
	v_pk_fma_f32 v[30:31], v[38:39], v[190:191], v[30:31] op_sel_hi:[1,0,1] neg_lo:[0,0,1] neg_hi:[0,0,1]
	v_pk_mul_f32 v[88:89], v[64:65], v[84:85]
	v_pk_mul_f32 v[84:85], v[64:65], v[84:85] op_sel:[1,0] op_sel_hi:[0,1]
	v_mov_b32_e32 v37, v31
	v_pk_mul_f32 v[30:31], v[40:41], v[52:53] op_sel_hi:[1,0]
	v_mov_b32_e32 v180, v178
	v_pk_fma_f32 v[38:39], v[40:41], v[64:65], v[30:31] op_sel:[0,0,1] op_sel_hi:[1,1,0]
	v_pk_fma_f32 v[30:31], v[40:41], v[64:65], v[30:31] op_sel:[0,0,1] op_sel_hi:[1,0,0] neg_lo:[0,0,1] neg_hi:[0,0,1]
	v_pk_add_f32 v[40:41], v[84:85], v[84:85] op_sel:[0,1] op_sel_hi:[0,1]
	v_mov_b32_e32 v39, v31
	v_pk_add_f32 v[30:31], v[88:89], v[88:89] op_sel:[0,1] op_sel_hi:[0,1] neg_lo:[0,1] neg_hi:[0,1]
	v_pk_mul_f32 v[40:41], v[42:43], v[40:41] op_sel:[1,0] op_sel_hi:[0,1]
	v_mov_b32_e32 v181, v177
	v_pk_fma_f32 v[52:53], v[42:43], v[30:31], v[40:41]
	v_pk_fma_f32 v[30:31], v[42:43], v[30:31], v[40:41] neg_lo:[0,0,1] neg_hi:[0,0,1]
	v_pk_mul_f32 v[182:183], v[64:65], v[180:181]
	v_pk_mul_f32 v[180:181], v[64:65], v[180:181] op_sel:[1,0] op_sel_hi:[0,1]
	v_mov_b32_e32 v53, v31
	v_pk_mul_f32 v[30:31], v[44:45], v[90:91] op_sel:[1,1] op_sel_hi:[0,1]
	v_pk_fma_f32 v[40:41], v[44:45], v[92:93], v[30:31]
	v_pk_fma_f32 v[30:31], v[44:45], v[92:93], v[30:31] op_sel_hi:[1,0,1] neg_lo:[0,0,1] neg_hi:[0,0,1]
	v_pk_add_f32 v[42:43], v[180:181], v[180:181] op_sel:[0,1] op_sel_hi:[0,1]
	v_mov_b32_e32 v41, v31
	v_pk_add_f32 v[30:31], v[182:183], v[182:183] op_sel:[0,1] op_sel_hi:[0,1] neg_lo:[0,1] neg_hi:[0,1]
	s_waitcnt lgkmcnt(4)
	v_pk_mul_f32 v[42:43], v[54:55], v[42:43] op_sel:[1,0] op_sel_hi:[0,1]
	v_mov_b32_e32 v172, v170
	v_mov_b32_e32 v173, v95
	v_pk_fma_f32 v[44:45], v[54:55], v[30:31], v[42:43]
	v_pk_fma_f32 v[30:31], v[54:55], v[30:31], v[42:43] neg_lo:[0,0,1] neg_hi:[0,0,1]
	v_pk_mul_f32 v[174:175], v[64:65], v[172:173]
	v_pk_mul_f32 v[172:173], v[64:65], v[172:173] op_sel:[1,0] op_sel_hi:[0,1]
	v_mov_b32_e32 v45, v31
	s_waitcnt lgkmcnt(3)
	v_pk_mul_f32 v[30:31], v[56:57], v[76:77] op_sel:[1,1] op_sel_hi:[0,1]
	v_pk_fma_f32 v[42:43], v[56:57], v[78:79], v[30:31]
	v_pk_fma_f32 v[30:31], v[56:57], v[78:79], v[30:31] op_sel_hi:[1,0,1] neg_lo:[0,0,1] neg_hi:[0,0,1]
	v_pk_add_f32 v[54:55], v[172:173], v[172:173] op_sel:[0,1] op_sel_hi:[0,1]
	v_mov_b32_e32 v43, v31
	v_pk_add_f32 v[30:31], v[174:175], v[174:175] op_sel:[0,1] op_sel_hi:[0,1] neg_lo:[0,1] neg_hi:[0,1]
	s_waitcnt lgkmcnt(2)
	v_pk_mul_f32 v[54:55], v[58:59], v[54:55] op_sel:[1,0] op_sel_hi:[0,1]
	v_mov_b32_e32 v192, v190
	v_mov_b32_e32 v193, v189
	v_pk_fma_f32 v[56:57], v[58:59], v[30:31], v[54:55]
	v_pk_fma_f32 v[30:31], v[58:59], v[30:31], v[54:55] neg_lo:[0,0,1] neg_hi:[0,0,1]
	v_pk_mul_f32 v[194:195], v[64:65], v[192:193]
	v_pk_mul_f32 v[192:193], v[64:65], v[192:193] op_sel:[1,0] op_sel_hi:[0,1]
	v_mov_b32_e32 v57, v31
	s_waitcnt lgkmcnt(1)
	v_pk_mul_f32 v[30:31], v[60:61], v[184:185] op_sel:[1,1] op_sel_hi:[0,1]
	v_pk_fma_f32 v[54:55], v[60:61], v[186:187], v[30:31]
	v_pk_fma_f32 v[30:31], v[60:61], v[186:187], v[30:31] op_sel_hi:[1,0,1] neg_lo:[0,0,1] neg_hi:[0,0,1]
	v_pk_add_f32 v[58:59], v[192:193], v[192:193] op_sel:[0,1] op_sel_hi:[0,1]
	v_mov_b32_e32 v55, v31
	v_pk_add_f32 v[30:31], v[194:195], v[194:195] op_sel:[0,1] op_sel_hi:[0,1] neg_lo:[0,1] neg_hi:[0,1]
	s_waitcnt lgkmcnt(0)
	v_pk_mul_f32 v[58:59], v[62:63], v[58:59] op_sel:[1,0] op_sel_hi:[0,1]
	v_pk_fma_f32 v[60:61], v[62:63], v[30:31], v[58:59]
	v_pk_fma_f32 v[30:31], v[62:63], v[30:31], v[58:59] neg_lo:[0,0,1] neg_hi:[0,0,1]
	v_pk_add_f32 v[58:59], v[70:71], v[50:51]
	v_mov_b32_e32 v61, v31
	v_pk_add_f32 v[30:31], v[46:47], v[196:197]
	v_pk_add_f32 v[50:51], v[70:71], v[50:51] neg_lo:[0,1] neg_hi:[0,1]
	v_pk_add_f32 v[46:47], v[46:47], v[196:197] neg_lo:[0,1] neg_hi:[0,1]
	v_pk_add_f32 v[62:63], v[48:49], v[32:33]
	v_pk_add_f32 v[32:33], v[48:49], v[32:33] neg_lo:[0,1] neg_hi:[0,1]
	v_pk_add_f32 v[48:49], v[34:35], v[36:37]
	v_pk_add_f32 v[34:35], v[34:35], v[36:37] neg_lo:[0,1] neg_hi:[0,1]
	v_pk_add_f32 v[36:37], v[38:39], v[52:53]
	v_pk_add_f32 v[38:39], v[38:39], v[52:53] neg_lo:[0,1] neg_hi:[0,1]
	v_pk_add_f32 v[52:53], v[40:41], v[44:45]
	v_pk_add_f32 v[40:41], v[40:41], v[44:45] neg_lo:[0,1] neg_hi:[0,1]
	v_pk_add_f32 v[44:45], v[42:43], v[56:57]
	v_pk_add_f32 v[42:43], v[42:43], v[56:57] neg_lo:[0,1] neg_hi:[0,1]
	v_pk_add_f32 v[56:57], v[54:55], v[60:61]
	v_pk_add_f32 v[54:55], v[54:55], v[60:61] neg_lo:[0,1] neg_hi:[0,1]
	v_pk_add_f32 v[60:61], v[30:31], v[58:59]
	v_pk_add_f32 v[30:31], v[30:31], v[58:59] neg_lo:[0,1] neg_hi:[0,1]
	v_xor_b32_e32 v58, 0x80000000, v51
	v_mov_b32_e32 v59, v50
	v_pk_add_f32 v[50:51], v[46:47], v[58:59]
	v_pk_add_f32 v[46:47], v[46:47], v[58:59] neg_lo:[0,1] neg_hi:[0,1]
	v_pk_add_f32 v[58:59], v[62:63], v[48:49]
	v_pk_add_f32 v[48:49], v[62:63], v[48:49] neg_lo:[0,1] neg_hi:[0,1]
	v_xor_b32_e32 v62, 0x80000000, v35
	v_mov_b32_e32 v63, v34
	v_pk_add_f32 v[34:35], v[32:33], v[62:63]
	v_pk_add_f32 v[32:33], v[32:33], v[62:63] neg_lo:[0,1] neg_hi:[0,1]
	v_pk_add_f32 v[62:63], v[36:37], v[52:53]
	v_pk_add_f32 v[36:37], v[36:37], v[52:53] neg_lo:[0,1] neg_hi:[0,1]
	v_xor_b32_e32 v52, 0x80000000, v41
	v_mov_b32_e32 v53, v40
	v_pk_add_f32 v[40:41], v[38:39], v[52:53]
	v_pk_add_f32 v[38:39], v[38:39], v[52:53] neg_lo:[0,1] neg_hi:[0,1]
	v_pk_add_f32 v[52:53], v[44:45], v[56:57]
	v_pk_add_f32 v[44:45], v[44:45], v[56:57] neg_lo:[0,1] neg_hi:[0,1]
	v_xor_b32_e32 v56, 0x80000000, v55
	v_mov_b32_e32 v57, v54
	v_pk_add_f32 v[54:55], v[42:43], v[56:57]
	v_pk_add_f32 v[42:43], v[42:43], v[56:57] neg_lo:[0,1] neg_hi:[0,1]
	v_pk_add_f32 v[56:57], v[60:61], v[58:59]
	v_pk_add_f32 v[58:59], v[60:61], v[58:59] neg_lo:[0,1] neg_hi:[0,1]
	v_pk_mul_f32 v[60:61], v[34:35], s[22:23] op_sel_hi:[1,0]
	s_cmpk_eq_i32 s78, 0x2000
	v_pk_fma_f32 v[64:65], v[34:35], s[22:23], v[60:61] op_sel:[0,0,1] op_sel_hi:[1,0,0] neg_lo:[0,0,1] neg_hi:[0,0,1]
	v_pk_fma_f32 v[34:35], v[34:35], s[22:23], v[60:61] op_sel_hi:[1,0,0]
	v_xor_b32_e32 v60, 0x80000000, v49
	v_mov_b32_e32 v61, v48
	v_pk_add_f32 v[48:49], v[30:31], v[60:61]
	v_pk_add_f32 v[30:31], v[30:31], v[60:61] neg_lo:[0,1] neg_hi:[0,1]
	v_mul_f32_e32 v60, 0x3f3504f3, v33
	v_pk_fma_f32 v[32:33], v[32:33], s[28:29], v[60:61] op_sel_hi:[0,1,0] neg_lo:[0,0,1] neg_hi:[0,0,1]
	v_mov_b32_e32 v65, v35
	v_pk_add_f32 v[60:61], v[46:47], v[32:33]
	v_pk_add_f32 v[32:33], v[46:47], v[32:33] neg_lo:[0,1] neg_hi:[0,1]
	v_pk_add_f32 v[46:47], v[62:63], v[52:53]
	v_pk_add_f32 v[52:53], v[62:63], v[52:53] neg_lo:[0,1] neg_hi:[0,1]
	v_pk_mul_f32 v[62:63], v[54:55], s[22:23] op_sel_hi:[1,0]
	v_pk_add_f32 v[34:35], v[50:51], v[64:65]
	v_pk_add_f32 v[50:51], v[50:51], v[64:65] neg_lo:[0,1] neg_hi:[0,1]
	v_pk_fma_f32 v[64:65], v[54:55], s[22:23], v[62:63] op_sel:[0,0,1] op_sel_hi:[1,0,0] neg_lo:[0,0,1] neg_hi:[0,0,1]
	v_pk_fma_f32 v[54:55], v[54:55], s[22:23], v[62:63] op_sel_hi:[1,0,0]
	v_xor_b32_e32 v62, 0x80000000, v45
	v_mov_b32_e32 v63, v44
	v_mov_b32_e32 v65, v55
	v_pk_add_f32 v[44:45], v[36:37], v[62:63]
	v_pk_add_f32 v[36:37], v[36:37], v[62:63] neg_lo:[0,1] neg_hi:[0,1]
	v_mul_f32_e32 v62, 0x3f3504f3, v43
	v_pk_add_f32 v[54:55], v[40:41], v[64:65]
	v_pk_fma_f32 v[42:43], v[42:43], s[28:29], v[62:63] op_sel_hi:[0,1,0] neg_lo:[0,0,1] neg_hi:[0,0,1]
	v_pk_add_f32 v[62:63], v[38:39], v[42:43]
	v_pk_add_f32 v[38:39], v[38:39], v[42:43] neg_lo:[0,1] neg_hi:[0,1]
	v_pk_add_f32 v[42:43], v[56:57], v[46:47]
	v_pk_mul_f32 v[46:47], v[54:55], s[16:17] op_sel_hi:[1,0]
	v_pk_add_f32 v[40:41], v[40:41], v[64:65] neg_lo:[0,1] neg_hi:[0,1]
	v_pk_fma_f32 v[56:57], v[54:55], s[18:19], v[46:47] op_sel:[0,0,1] op_sel_hi:[1,0,0] neg_lo:[0,0,1] neg_hi:[0,0,1]
	v_pk_fma_f32 v[46:47], v[54:55], s[18:19], v[46:47] op_sel:[0,0,1] op_sel_hi:[1,0,0]
	s_waitcnt vmcnt(16)
	v_fma_f32 v28, v136, v28, v42
	v_mov_b32_e32 v57, v47
	v_pk_mul_f32 v[46:47], v[44:45], s[22:23] op_sel_hi:[1,0]
	v_fmac_f32_e32 v43, v136, v29
	v_pk_fma_f32 v[54:55], v[44:45], s[22:23], v[46:47] op_sel:[0,0,1] op_sel_hi:[1,0,0] neg_lo:[0,0,1] neg_hi:[0,0,1]
	v_pk_fma_f32 v[44:45], v[44:45], s[22:23], v[46:47] op_sel_hi:[1,0,0]
	v_pk_mul_f32 v[46:47], v[62:63], s[18:19] op_sel_hi:[1,0]
	v_mov_b32_e32 v55, v45
	v_pk_add_f32 v[44:45], v[48:49], v[54:55]
	v_pk_fma_f32 v[48:49], v[62:63], s[16:17], v[46:47] op_sel:[0,0,1] op_sel_hi:[1,0,0] neg_lo:[0,0,1] neg_hi:[0,0,1]
	v_pk_fma_f32 v[46:47], v[62:63], s[16:17], v[46:47] op_sel:[0,0,1] op_sel_hi:[1,0,0]
	v_pk_add_f32 v[34:35], v[34:35], v[56:57]
	v_mov_b32_e32 v49, v47
	v_pk_add_f32 v[46:47], v[60:61], v[48:49]
	v_xor_b32_e32 v48, 0x80000000, v53
	v_mov_b32_e32 v49, v52
	v_pk_mul_f32 v[52:53], v[40:41], s[18:19] op_sel:[1,0]
	v_fma_f32 v24, v136, v24, v34
	v_pk_fma_f32 v[40:41], v[40:41], s[30:31], v[52:53] op_sel_hi:[0,1,1] neg_lo:[0,0,1] neg_hi:[0,0,1]
	v_pk_add_f32 v[40:41], v[50:51], v[40:41]
	v_mul_f32_e32 v50, 0x3f3504f3, v37
	v_pk_fma_f32 v[36:37], v[36:37], s[28:29], v[50:51] op_sel_hi:[0,1,0] neg_lo:[0,0,1] neg_hi:[0,0,1]
	v_pk_add_f32 v[30:31], v[30:31], v[36:37]
	v_pk_mul_f32 v[36:37], v[38:39], s[16:17] op_sel:[1,0]
	s_waitcnt vmcnt(12)
	v_lshlrev_b32_e32 v34, 16, v165
	v_pk_fma_f32 v[36:37], v[38:39], s[24:25], v[36:37] op_sel_hi:[0,1,1] neg_lo:[0,0,1] neg_hi:[0,0,1]
	v_pk_add_f32 v[32:33], v[32:33], v[36:37]
	v_lshlrev_b32_e32 v36, 16, v168
	v_mul_f32_e32 v28, v28, v36
	v_lshlrev_b32_e32 v36, 16, v167
	v_bfe_u32 v29, v28, 16, 1
	v_mul_f32_e32 v36, v43, v36
	v_add3_u32 v37, v28, v29, s45
	v_lshl_add_u64 v[28:29], s[72:73], 1, v[4:5]
	global_store_short_d16_hi v[28:29], v37, off
	v_bfe_u32 v37, v36, 16, 1
	v_add3_u32 v38, v36, v37, s45
	v_lshl_add_u64 v[36:37], s[58:59], 1, v[4:5]
	global_store_short_d16_hi v[36:37], v38, off
	v_lshlrev_b32_e32 v38, 16, v166
	v_mul_f32_e32 v24, v24, v38
	v_fmac_f32_e32 v35, v136, v25
	v_mul_f32_e32 v25, v35, v34
	v_bfe_u32 v34, v24, 16, 1
	v_add3_u32 v24, v24, v34, s45
	global_store_short_d16_hi v[28:29], v24, off offset:1024
	v_bfe_u32 v24, v25, 16, 1
	v_add3_u32 v24, v25, v24, s45
	global_store_short_d16_hi v[36:37], v24, off offset:1024
	s_waitcnt vmcnt(15)
	v_lshlrev_b32_e32 v24, 16, v164
	v_fma_f32 v22, v136, v22, v44
	v_mul_f32_e32 v22, v22, v24
	s_waitcnt vmcnt(14)
	v_lshlrev_b32_e32 v24, 16, v163
	v_fmac_f32_e32 v45, v136, v23
	v_mul_f32_e32 v23, v45, v24
	v_bfe_u32 v24, v22, 16, 1
	v_add3_u32 v22, v22, v24, s45
	global_store_short_d16_hi v[28:29], v22, off offset:2048
	v_bfe_u32 v22, v23, 16, 1
	v_add3_u32 v22, v23, v22, s45
	global_store_short_d16_hi v[36:37], v22, off offset:2048
	s_waitcnt vmcnt(14)
	v_lshlrev_b32_e32 v22, 16, v162
	v_fma_f32 v20, v136, v20, v46
	v_mul_f32_e32 v20, v20, v22
	v_lshlrev_b32_e32 v22, 16, v159
	v_fmac_f32_e32 v47, v136, v21
	v_mul_f32_e32 v21, v47, v22
	v_bfe_u32 v22, v20, 16, 1
	v_add3_u32 v20, v20, v22, s45
	global_store_short_d16_hi v[28:29], v20, off offset:3072
	v_bfe_u32 v20, v21, 16, 1
	v_pk_add_f32 v[48:49], v[58:59], v[48:49]
	v_add3_u32 v20, v21, v20, s45
	global_store_short_d16_hi v[36:37], v20, off offset:3072
	s_waitcnt vmcnt(15)
	v_lshlrev_b32_e32 v20, 16, v160
	v_fma_f32 v18, v136, v18, v48
	v_mul_f32_e32 v18, v18, v20
	v_fmac_f32_e32 v49, v136, v19
	v_bfe_u32 v19, v18, 16, 1
	s_waitcnt vmcnt(14)
	v_lshlrev_b32_e32 v20, 16, v161
	v_add3_u32 v21, v18, v19, s45
	v_add_co_u32_e32 v18, vcc, s39, v28
	v_mul_f32_e32 v20, v49, v20
	s_nop 0
	v_addc_co_u32_e32 v19, vcc, 0, v29, vcc
	global_store_short_d16_hi v[18:19], v21, off
	v_bfe_u32 v21, v20, 16, 1
	v_add3_u32 v22, v20, v21, s45
	v_add_co_u32_e32 v20, vcc, s39, v36
	v_fma_f32 v6, v136, v6, v40
	s_nop 0
	v_addc_co_u32_e32 v21, vcc, 0, v37, vcc
	global_store_short_d16_hi v[20:21], v22, off
	s_waitcnt vmcnt(15)
	v_lshlrev_b32_e32 v22, 16, v158
	v_mul_f32_e32 v6, v6, v22
	s_waitcnt vmcnt(14)
	v_lshlrev_b32_e32 v22, 16, v157
	v_fmac_f32_e32 v41, v136, v7
	v_mul_f32_e32 v7, v41, v22
	v_bfe_u32 v22, v6, 16, 1
	v_add3_u32 v6, v6, v22, s45
	global_store_short_d16_hi v[18:19], v6, off offset:1024
	v_bfe_u32 v6, v7, 16, 1
	v_add3_u32 v6, v7, v6, s45
	global_store_short_d16_hi v[20:21], v6, off offset:1024
	s_waitcnt vmcnt(15)
	v_lshlrev_b32_e32 v6, 16, v156
	v_fma_f32 v7, v136, v16, v30
	v_mul_f32_e32 v6, v7, v6
	s_waitcnt vmcnt(14)
	v_lshlrev_b32_e32 v7, 16, v155
	v_fmac_f32_e32 v31, v136, v17
	v_bfe_u32 v16, v6, 16, 1
	v_mul_f32_e32 v7, v31, v7
	v_add3_u32 v6, v6, v16, s45
	global_store_short_d16_hi v[18:19], v6, off offset:2048
	v_bfe_u32 v6, v7, 16, 1
	v_add3_u32 v6, v7, v6, s45
	global_store_short_d16_hi v[20:21], v6, off offset:2048
	s_waitcnt vmcnt(14)
	v_lshlrev_b32_e32 v6, 16, v154
	v_fma_f32 v7, v136, v8, v32
	v_mul_f32_e32 v6, v7, v6
	v_lshlrev_b32_e32 v7, 16, v153
	v_fmac_f32_e32 v33, v136, v9
	v_bfe_u32 v8, v6, 16, 1
	v_mul_f32_e32 v7, v33, v7
	v_add3_u32 v6, v6, v8, s45
	global_store_short_d16_hi v[18:19], v6, off offset:3072
	v_bfe_u32 v6, v7, 16, 1
	v_add3_u32 v6, v7, v6, s45
	v_mov_b32_e32 v66, v138
	v_mov_b32_e32 v67, v139
	v_mov_b32_e32 v68, v140
	v_mov_b32_e32 v69, v142
	v_mov_b32_e32 v71, v146
	v_mov_b32_e32 v72, v147
	v_mov_b32_e32 v62, v148
	v_mov_b32_e32 v63, v150
	v_mov_b32_e32 v70, v137
	v_mov_b32_e32 v73, v141
	v_mov_b32_e32 v74, v143
	v_mov_b32_e32 v75, v144
	v_mov_b32_e32 v76, v145
	v_mov_b32_e32 v77, v149
	v_mov_b32_e32 v64, v151
	v_mov_b32_e32 v65, v152
	global_store_short_d16_hi v[20:21], v6, off offset:3072
	s_cbranch_scc1 .LBB0_1150

.LBB0_1580:
	s_cmpk_lt_u32 s2, 0x80
	s_cselect_b64 s[4:5], -1, 0
	s_cmpk_gt_u32 s2, 0x7f
	s_cselect_b64 s[10:11], -1, 0
	s_mov_b32 s3, 0xcc00
	s_and_b64 s[6:7], s[10:11], exec
	s_cselect_b32 s12, s3, 0xcc00
	s_add_i32 s13, s54, 0x6000
	s_cmpk_eq_i32 s56, 0x100
	s_cselect_b64 s[6:7], -1, 0
	s_mov_b32 s18, 0xc000
	s_and_b64 s[8:9], s[6:7], exec
	s_cselect_b32 s19, 0xcc00, s18
	s_cselect_b32 s20, s12, s13
	s_movk_i32 s3, 0x6000
	s_cmp_ge_u32 s20, s19
	s_waitcnt vmcnt(0)
	s_barrier
	s_cbranch_scc1 .LBB0_1595
	v_readlane_b32 s8, v255, 7
	s_and_b32 s8, s8, 0x3f8
	v_readlane_b32 s13, v255, 6
	s_add_i32 s21, s13, s8
	s_lshl_b32 s22, s21, 1
	s_movk_i32 s12, 0x800
	s_and_b64 s[8:9], s[10:11], exec
	s_cselect_b32 s12, s12, 0x400
	s_and_b64 s[8:9], s[6:7], exec
	s_mul_i32 s8, s13, 0x2200
	s_cselect_b32 s23, s12, s55
	s_add_i32 s25, s8, 0
	v_cndmask_b32_e64 v2, 0, 1, s[4:5]
	v_and_b32_e32 v1, 63, v0
	s_mov_b32 s9, 0
	s_mov_b32 s24, 0x10000
	s_add_i32 s25, s25, 0x10000
	s_and_b64 s[10:11], s[10:11], s[6:7]
	v_cmp_ne_u32_e64 s[4:5], 1, v2
	v_mov_b32_e32 v3, 0
	s_movk_i32 s26, 0x2000
	s_movk_i32 s27, 0x4000
	s_mov_b32 s28, 0x8000
	s_mov_b32 s29, 0xa000
	s_mov_b32 s30, 0xe000
	s_mov_b32 s31, 0x12000
	s_mov_b32 s34, 0x14000
	s_mov_b32 s35, 0x16000
	s_mov_b32 s36, 0x18000
	s_mov_b32 s37, 0x1a000
	s_mov_b32 s38, 0x1c000
	s_mov_b32 s39, 0x1e000
	s_mov_b32 s41, 0x20000
	s_mov_b32 s42, 0x22000
	s_mov_b32 s43, 0x24000
	s_mov_b32 s45, 0x26000
	s_mov_b32 s46, 0x28000
	s_mov_b32 s47, 0x2a000
	s_mov_b32 s49, 0x2c000
	s_mov_b32 s57, 0x2e000
	s_mov_b32 s58, 0x30000
	s_mov_b32 s59, 0x32000
	s_mov_b32 s72, 0x34000
	s_mov_b32 s73, 0x36000
	s_mov_b32 s78, 0x38000
	s_mov_b32 s79, 0x3a000
	s_mov_b32 s84, 0x3c000
	s_mov_b32 s85, 0x3e000
	s_movk_i32 s86, 0x84
	s_branch .LBB0_1583

.LBB0_2349:
	s_cmpk_lt_u32 s2, 0x80
	s_cselect_b64 s[4:5], -1, 0
	s_cmpk_gt_u32 s2, 0x7f
	s_cselect_b64 s[10:11], -1, 0
	s_mov_b32 s3, 0x13900
	s_and_b64 s[6:7], s[10:11], exec
	s_cselect_b32 s12, s3, 0x13900
	s_mov_b32 s3, 0x13900
	s_cselect_b32 s13, 0x13900, s3
	s_add_i32 s14, s54, 0xc000
	s_cmpk_eq_i32 s56, 0x100
	s_cselect_b64 s[6:7], -1, 0
	s_and_b64 s[8:9], s[6:7], exec
	s_cselect_b32 s18, s13, 0x12000
	s_cselect_b32 s19, s12, s14
	s_mov_b32 s3, 0xc000
	s_cmp_ge_u32 s19, s18
	s_mov_b32 s20, 0x12000
	s_waitcnt vmcnt(0)
	s_barrier
	s_cbranch_scc1 .LBB0_2364
	v_readlane_b32 s8, v255, 7
	s_and_b32 s8, s8, 0x3f8
	v_readlane_b32 s13, v255, 6
	s_add_i32 s21, s13, s8
	s_lshl_b32 s22, s21, 1
	s_movk_i32 s12, 0x800
	s_and_b64 s[8:9], s[10:11], exec
	s_cselect_b32 s12, s12, 0x400
	s_and_b64 s[8:9], s[6:7], exec
	s_mul_i32 s8, s13, 0x2200
	s_cselect_b32 s23, s12, s55
	s_add_i32 s25, s8, 0
	v_cndmask_b32_e64 v2, 0, 1, s[4:5]
	v_and_b32_e32 v1, 63, v0
	s_mov_b32 s9, 0
	s_mov_b32 s24, 0x10000
	s_add_i32 s25, s25, 0x10000
	s_and_b64 s[10:11], s[10:11], s[6:7]
	v_cmp_ne_u32_e64 s[4:5], 1, v2
	v_mov_b32_e32 v3, 0
	s_movk_i32 s26, 0x2000
	s_movk_i32 s27, 0x4000
	s_movk_i32 s28, 0x6000
	s_mov_b32 s29, 0x8000
	s_mov_b32 s30, 0xa000
	s_mov_b32 s31, 0xe000
	s_mov_b32 s34, 0x14000
	s_mov_b32 s35, 0x16000
	s_mov_b32 s36, 0x18000
	s_mov_b32 s37, 0x1a000
	s_mov_b32 s38, 0x1c000
	s_mov_b32 s39, 0x1e000
	s_mov_b32 s41, 0x20000
	s_mov_b32 s42, 0x22000
	s_mov_b32 s43, 0x24000
	s_mov_b32 s45, 0x26000
	s_mov_b32 s46, 0x28000
	s_mov_b32 s47, 0x2a000
	s_mov_b32 s49, 0x2c000
	s_mov_b32 s57, 0x2e000
	s_mov_b32 s58, 0x30000
	s_mov_b32 s59, 0x32000
	s_mov_b32 s72, 0x34000
	s_mov_b32 s73, 0x36000
	s_mov_b32 s78, 0x38000
	s_mov_b32 s79, 0x3a000
	s_mov_b32 s84, 0x3c000
	s_mov_b32 s85, 0x3e000
	s_movk_i32 s86, 0x84
	s_branch .LBB0_2352

.LBB0_3025:
	s_cmpk_lt_u32 s2, 0x80
	s_cselect_b64 s[4:5], -1, 0
	s_cmpk_gt_u32 s2, 0x7f
	s_cselect_b64 s[10:11], -1, 0
	s_mov_b32 s3, 0x18000
	s_and_b64 s[6:7], s[10:11], exec
	s_cselect_b32 s12, s3, 0x18000
	s_add_i32 s13, s54, 0x12000
	s_cmpk_eq_i32 s56, 0x100
	s_cselect_b64 s[6:7], -1, 0
	s_and_b64 s[8:9], s[6:7], exec
	s_cselect_b32 s18, s12, s13
	s_and_b64 s[8:9], s[10:11], s[6:7]
	s_mov_b32 s19, 0x18000
	s_and_b64 s[12:13], s[8:9], exec
	s_cselect_b32 s20, 0x18000, s19
	s_mov_b32 s3, 0x12000
	s_cmp_ge_u32 s18, s20
	s_waitcnt vmcnt(0)
	s_barrier
	s_cbranch_scc1 .LBB0_3040
	v_readlane_b32 s12, v255, 7
	s_and_b32 s12, s12, 0x3f8
	v_readlane_b32 s13, v255, 6
	s_add_i32 s21, s13, s12
	s_lshl_b32 s22, s21, 1
	s_movk_i32 s12, 0x800
	s_and_b64 s[10:11], s[10:11], exec
	s_cselect_b32 s12, s12, 0x400
	s_and_b64 s[10:11], s[6:7], exec
	s_mul_i32 s10, s13, 0x2200
	s_cselect_b32 s23, s12, s55
	s_add_i32 s25, s10, 0
	v_cndmask_b32_e64 v2, 0, 1, s[4:5]
	s_mov_b32 s11, 0
	s_mov_b32 s24, 0x10000
	s_add_i32 s25, s25, 0x10000
	v_cmp_ne_u32_e64 s[4:5], 1, v2
	v_mov_b32_e32 v3, 0
	s_movk_i32 s26, 0x2000
	s_movk_i32 s27, 0x4000
	s_movk_i32 s28, 0x6000
	s_mov_b32 s29, 0x8000
	s_mov_b32 s30, 0xa000
	s_mov_b32 s31, 0xc000
	s_mov_b32 s34, 0xe000
	s_mov_b32 s35, 0x14000
	s_mov_b32 s36, 0x16000
	s_mov_b32 s37, 0x1a000
	s_mov_b32 s38, 0x1c000
	s_mov_b32 s39, 0x1e000
	s_mov_b32 s41, 0x20000
	s_mov_b32 s42, 0x22000
	s_mov_b32 s43, 0x24000
	s_mov_b32 s45, 0x26000
	s_mov_b32 s46, 0x28000
	s_mov_b32 s47, 0x2a000
	s_mov_b32 s50, 0x2c000
	s_mov_b32 s51, 0x2e000
	s_mov_b32 s57, 0x30000
	s_mov_b32 s58, 0x32000
	s_mov_b32 s59, 0x34000
	s_mov_b32 s72, 0x36000
	s_mov_b32 s73, 0x38000
	s_mov_b32 s76, 0x3a000
	s_mov_b32 s77, 0x3c000
	s_mov_b32 s78, 0x3e000
	s_movk_i32 s79, 0x84
	s_movk_i32 s80, 0xc8
	s_branch .LBB0_3028
